# GU epilogue: shift vectors prefetched at unit head, no full vmcnt drain (on top of SCAN rewrite)
# baseline (speedup 1.0000x reference)
.LBB0_731:
	v_lshl_add_u32 v154, s64, 8, v161
	v_ashrrev_i32_e32 v155, 31, v154
	v_lshl_add_u64 v[0:1], v[154:155], 2, s[52:53]
	global_load_dword v156, v[0:1], off
	global_load_dword v158, v[0:1], off offset:64
	global_load_dword v175, v[0:1], off offset:128
	global_load_dword v174, v[0:1], off offset:192
	global_load_dword v167, v[0:1], off offset:512
	global_load_dword v166, v[0:1], off offset:576
	global_load_dword v165, v[0:1], off offset:640
	global_load_dword v155, v[0:1], off offset:704
	s_ashr_i32 s46, s64, 4
	v_lshl_or_b32 v6, s77, 7, v163
	s_mul_i32 s59, s46, 0x3800
	s_mul_hi_i32 s57, s46, 0x3800
	s_add_u32 s46, s39, s59
	v_ashrrev_i32_e32 v7, 31, v6
	s_addc_u32 s47, s41, s57
	v_lshlrev_b64 v[2:3], 2, v[6:7]
	v_lshl_add_u64 v[4:5], s[46:47], 0, v[2:3]
	global_load_dwordx4 v[246:249], v[4:5], off
	global_load_dwordx4 v[242:245], v[4:5], off offset:16
	s_add_u32 s46, s95, s59
	s_addc_u32 s47, s89, s57
	v_lshl_add_u64 v[2:3], s[46:47], 0, v[2:3]
	global_load_dwordx4 v[238:241], v[2:3], off
	global_load_dwordx4 v[234:237], v[2:3], off offset:16
	s_ashr_i32 s59, s58, 31
	s_lshl_b64 s[46:47], s[58:59], 19
	s_add_u32 s60, s29, s46
	s_addc_u32 s61, s72, s47
	s_and_b64 s[46:47], s[4:5], exec
	s_cselect_b32 s59, s61, s69
	s_cselect_b32 vcc_lo, s60, s68
	s_ashr_i32 s57, s56, 31
	s_lshl_b64 s[46:47], s[56:57], 19
	s_add_u32 s62, s73, s46
	s_addc_u32 s63, s78, s47
	s_and_b64 s[46:47], s[4:5], exec
	s_cselect_b32 s57, s63, s67
	s_cselect_b32 vcc_hi, s62, s66
	s_add_u32 s96, s66, 0x100
	s_addc_u32 s84, s67, 0
	s_add_u32 s66, s68, 0x40080
	v_mov_b32_e32 v0, 0
	s_addc_u32 s67, s69, 0
	s_mov_b32 s46, -2
	v_mov_b32_e32 v1, v0
	v_mov_b32_e32 v2, v0
	v_mov_b32_e32 v3, v0
	v_mov_b32_e32 v4, v0
	v_mov_b32_e32 v5, v0
	v_mov_b32_e32 v6, v0
	v_mov_b32_e32 v7, v0
	v_mov_b32_e32 v16, v0
	v_mov_b32_e32 v17, v0
	v_mov_b32_e32 v18, v0
	v_mov_b32_e32 v19, v0
	v_mov_b32_e32 v20, v0
	v_mov_b32_e32 v21, v0
	v_mov_b32_e32 v22, v0
	v_mov_b32_e32 v23, v0
	v_mov_b32_e32 v32, v0
	v_mov_b32_e32 v33, v0
	v_mov_b32_e32 v34, v0
	v_mov_b32_e32 v35, v0
	v_mov_b32_e32 v36, v0
	v_mov_b32_e32 v37, v0
	v_mov_b32_e32 v38, v0
	v_mov_b32_e32 v39, v0
	v_mov_b32_e32 v48, v0
	v_mov_b32_e32 v49, v0
	v_mov_b32_e32 v50, v0
	v_mov_b32_e32 v51, v0
	v_mov_b32_e32 v52, v0
	v_mov_b32_e32 v53, v0
	v_mov_b32_e32 v54, v0
	v_mov_b32_e32 v55, v0
	v_mov_b32_e32 v8, v0
	v_mov_b32_e32 v9, v0
	v_mov_b32_e32 v10, v0
	v_mov_b32_e32 v11, v0
	v_mov_b32_e32 v12, v0
	v_mov_b32_e32 v13, v0
	v_mov_b32_e32 v14, v0
	v_mov_b32_e32 v15, v0
	v_mov_b32_e32 v24, v0
	v_mov_b32_e32 v25, v0
	v_mov_b32_e32 v26, v0
	v_mov_b32_e32 v27, v0
	v_mov_b32_e32 v28, v0
	v_mov_b32_e32 v29, v0
	v_mov_b32_e32 v30, v0
	v_mov_b32_e32 v31, v0
	v_mov_b32_e32 v40, v0
	v_mov_b32_e32 v41, v0
	v_mov_b32_e32 v42, v0
	v_mov_b32_e32 v43, v0
	v_mov_b32_e32 v44, v0
	v_mov_b32_e32 v45, v0
	v_mov_b32_e32 v46, v0
	v_mov_b32_e32 v47, v0
	v_mov_b32_e32 v56, v0
	v_mov_b32_e32 v57, v0
	v_mov_b32_e32 v58, v0
	v_mov_b32_e32 v59, v0
	v_mov_b32_e32 v60, v0
	v_mov_b32_e32 v61, v0
	v_mov_b32_e32 v62, v0
	v_mov_b32_e32 v63, v0
	v_mov_b32_e32 v64, v0
	v_mov_b32_e32 v65, v0
	v_mov_b32_e32 v66, v0
	v_mov_b32_e32 v67, v0
	v_mov_b32_e32 v68, v0
	v_mov_b32_e32 v69, v0
	v_mov_b32_e32 v70, v0
	v_mov_b32_e32 v71, v0
	v_mov_b32_e32 v80, v0
	v_mov_b32_e32 v81, v0
	v_mov_b32_e32 v82, v0
	v_mov_b32_e32 v83, v0
	v_mov_b32_e32 v84, v0
	v_mov_b32_e32 v85, v0
	v_mov_b32_e32 v86, v0
	v_mov_b32_e32 v87, v0
	s_waitcnt vmcnt(0)
	v_mov_b32_e32 v96, v0
	v_mov_b32_e32 v97, v0
	v_mov_b32_e32 v98, v0
	v_mov_b32_e32 v99, v0
	v_mov_b32_e32 v100, v0
	v_mov_b32_e32 v101, v0
	v_mov_b32_e32 v102, v0
	v_mov_b32_e32 v103, v0
	v_mov_b32_e32 v104, v0
	v_mov_b32_e32 v105, v0
	v_mov_b32_e32 v106, v0
	v_mov_b32_e32 v107, v0
	v_mov_b32_e32 v108, v0
	v_mov_b32_e32 v109, v0
	v_mov_b32_e32 v110, v0
	v_mov_b32_e32 v111, v0
	v_mov_b32_e32 v72, v0
	v_mov_b32_e32 v73, v0
	v_mov_b32_e32 v74, v0
	v_mov_b32_e32 v75, v0
	v_mov_b32_e32 v76, v0
	v_mov_b32_e32 v77, v0
	v_mov_b32_e32 v78, v0
	v_mov_b32_e32 v79, v0
	v_mov_b32_e32 v88, v0
	v_mov_b32_e32 v89, v0
	v_mov_b32_e32 v90, v0
	v_mov_b32_e32 v91, v0
	v_mov_b32_e32 v92, v0
	v_mov_b32_e32 v93, v0
	v_mov_b32_e32 v94, v0
	v_mov_b32_e32 v95, v0
	v_mov_b32_e32 v112, v0
	v_mov_b32_e32 v113, v0
	v_mov_b32_e32 v114, v0
	v_mov_b32_e32 v115, v0
	v_mov_b32_e32 v116, v0
	v_mov_b32_e32 v117, v0
	v_mov_b32_e32 v118, v0
	v_mov_b32_e32 v119, v0
	v_mov_b32_e32 v120, v0
	v_mov_b32_e32 v121, v0
	v_mov_b32_e32 v122, v0
	v_mov_b32_e32 v123, v0
	v_mov_b32_e32 v124, v0
	v_mov_b32_e32 v125, v0
	v_mov_b32_e32 v126, v0
	v_mov_b32_e32 v127, v0

.LBB0_735:
	v_lshl_or_b32 v170, s77, 7, v163
	v_ashrrev_i32_e32 v171, 31, v170
	v_fmamk_f32 v159, v156, 0x3a800000, v226
	v_fmamk_f32 v158, v158, 0x3a800000, v226
	v_rsq_f32_e32 v172, v159
	v_rsq_f32_e32 v178, v158
	v_add_u32_e32 v173, 0x80, v154
	v_mov_b64_e32 v[156:157], s[50:51]
	v_or_b32_e32 v179, 16, v154
	v_mad_i64_i32 v[176:177], s[46:47], v154, s88, v[156:157]
	v_lshlrev_b64 v[158:159], 1, v[170:171]
	v_mad_i64_i32 v[180:181], s[46:47], v179, s88, v[156:157]
	v_lshl_add_u64 v[170:171], v[176:177], 0, v[158:159]
	s_andn2_b64 vcc, exec, s[4:5]
	s_mov_b64 s[4:5], -1
	v_pk_fma_f32 v[126:127], v[172:173], v[126:127], v[248:249] op_sel_hi:[0,1,1]
	v_pk_fma_f32 v[124:125], v[172:173], v[124:125], v[246:247] op_sel_hi:[0,1,1]
	v_pk_fma_f32 v[122:123], v[172:173], v[122:123], v[244:245] op_sel_hi:[0,1,1]
	v_pk_fma_f32 v[120:121], v[172:173], v[120:121], v[242:243] op_sel_hi:[0,1,1]
	v_pk_fma_f32 v[118:119], v[178:179], v[118:119], v[248:249] op_sel_hi:[0,1,1]
	v_pk_fma_f32 v[116:117], v[178:179], v[116:117], v[246:247] op_sel_hi:[0,1,1]
	v_pk_fma_f32 v[114:115], v[178:179], v[114:115], v[244:245] op_sel_hi:[0,1,1]
	v_pk_fma_f32 v[112:113], v[178:179], v[112:113], v[242:243] op_sel_hi:[0,1,1]
	v_mul_f32_e32 v176, 0xbfb8aa3b, v124
	v_mul_f32_e32 v177, 0xbfb8aa3b, v120
	v_mul_f32_e32 v179, 0xbfb8aa3b, v125
	v_mul_f32_e32 v182, 0xbfb8aa3b, v121
	v_mul_f32_e32 v183, 0xbfb8aa3b, v126
	v_mul_f32_e32 v184, 0xbfb8aa3b, v122
	v_mul_f32_e32 v185, 0xbfb8aa3b, v127
	v_mul_f32_e32 v186, 0xbfb8aa3b, v123
	v_exp_f32_e32 v176, v176
	v_exp_f32_e32 v177, v177
	v_exp_f32_e32 v179, v179
	v_exp_f32_e32 v182, v182
	v_exp_f32_e32 v183, v183
	v_exp_f32_e32 v184, v184
	v_exp_f32_e32 v185, v185
	v_exp_f32_e32 v186, v186
	v_pk_fma_f32 v[110:111], v[172:173], v[110:111], v[240:241] op_sel_hi:[0,1,1]
	v_pk_fma_f32 v[108:109], v[172:173], v[108:109], v[238:239] op_sel_hi:[0,1,1]
	v_pk_fma_f32 v[106:107], v[172:173], v[106:107], v[236:237] op_sel_hi:[0,1,1]
	v_pk_fma_f32 v[104:105], v[172:173], v[104:105], v[234:235] op_sel_hi:[0,1,1]
	v_pk_mul_f32 v[110:111], v[126:127], v[110:111]
	v_pk_mul_f32 v[108:109], v[124:125], v[108:109]
	v_pk_mul_f32 v[106:107], v[122:123], v[106:107]
	v_pk_mul_f32 v[104:105], v[120:121], v[104:105]
	v_add_f32_e32 v120, 1.0, v176
	v_add_f32_e32 v121, 1.0, v177
	v_add_f32_e32 v123, 1.0, v179
	v_add_f32_e32 v176, 1.0, v182
	v_add_f32_e32 v124, 1.0, v183
	v_add_f32_e32 v126, 1.0, v184
	v_add_f32_e32 v125, 1.0, v185
	v_add_f32_e32 v127, 1.0, v186
	v_rcp_f32_e32 v120, v120
	v_rcp_f32_e32 v122, v121
	v_rcp_f32_e32 v121, v123
	v_rcp_f32_e32 v124, v124
	v_rcp_f32_e32 v125, v125
	v_rcp_f32_e32 v126, v126
	v_rcp_f32_e32 v127, v127
	v_rcp_f32_e32 v123, v176
	v_pk_mul_f32 v[110:111], v[110:111], v[124:125]
	v_pk_mul_f32 v[108:109], v[108:109], v[120:121]
	v_pk_mul_f32 v[120:121], v[106:107], v[126:127]
	v_pk_mul_f32 v[106:107], v[104:105], v[122:123]
	v_mul_f32_e32 v187, 0xbfb8aa3b, v116
	v_mul_f32_e32 v188, 0xbfb8aa3b, v112
	v_cvt_pk_bf16_f32 v104, v108, v109
	v_cvt_pk_bf16_f32 v105, v110, v111
	v_cvt_pk_bf16_f32 v106, v106, v107
	v_cvt_pk_bf16_f32 v107, v120, v121
	v_mul_f32_e32 v189, 0xbfb8aa3b, v117
	v_mul_f32_e32 v190, 0xbfb8aa3b, v113
	v_mul_f32_e32 v191, 0xbfb8aa3b, v118
	v_mul_f32_e32 v192, 0xbfb8aa3b, v114
	v_mul_f32_e32 v193, 0xbfb8aa3b, v119
	v_exp_f32_e32 v172, v187
	v_exp_f32_e32 v187, v188
	global_store_dwordx4 v[170:171], v[104:107], off
	v_exp_f32_e32 v188, v189
	v_exp_f32_e32 v189, v190
	v_mul_f32_e32 v104, 0xbfb8aa3b, v115
	v_exp_f32_e32 v190, v191
	v_exp_f32_e32 v191, v192
	v_exp_f32_e32 v109, v193
	v_exp_f32_e32 v111, v104
	v_add_f32_e32 v105, 1.0, v187
	v_add_f32_e32 v104, 1.0, v172
	v_rcp_f32_e32 v106, v105
	v_add_f32_e32 v105, 1.0, v188
	v_add_f32_e32 v107, 1.0, v189
	v_add_f32_e32 v108, 1.0, v190
	v_add_f32_e32 v110, 1.0, v191
	v_add_f32_e32 v109, 1.0, v109
	v_add_f32_e32 v111, 1.0, v111
	v_rcp_f32_e32 v104, v104
	v_rcp_f32_e32 v105, v105
	v_rcp_f32_e32 v107, v107
	v_rcp_f32_e32 v108, v108
	v_rcp_f32_e32 v110, v110
	v_rcp_f32_e32 v109, v109
	v_rcp_f32_e32 v111, v111
	v_pk_fma_f32 v[102:103], v[178:179], v[102:103], v[240:241] op_sel_hi:[0,1,1]
	v_pk_fma_f32 v[100:101], v[178:179], v[100:101], v[238:239] op_sel_hi:[0,1,1]
	v_pk_fma_f32 v[98:99], v[178:179], v[98:99], v[236:237] op_sel_hi:[0,1,1]
	v_pk_fma_f32 v[96:97], v[178:179], v[96:97], v[234:235] op_sel_hi:[0,1,1]
	v_pk_mul_f32 v[102:103], v[118:119], v[102:103]
	v_pk_mul_f32 v[100:101], v[116:117], v[100:101]
	v_pk_mul_f32 v[98:99], v[114:115], v[98:99]
	v_pk_mul_f32 v[96:97], v[112:113], v[96:97]
	v_pk_mul_f32 v[102:103], v[102:103], v[108:109]
	v_pk_mul_f32 v[100:101], v[100:101], v[104:105]
	v_pk_mul_f32 v[104:105], v[98:99], v[110:111]
	v_pk_mul_f32 v[98:99], v[96:97], v[106:107]
	v_lshl_add_u64 v[120:121], v[180:181], 0, v[158:159]
	v_cvt_pk_bf16_f32 v96, v100, v101
	v_cvt_pk_bf16_f32 v97, v102, v103
	v_cvt_pk_bf16_f32 v98, v98, v99
	v_cvt_pk_bf16_f32 v99, v104, v105
	global_store_dwordx4 v[120:121], v[96:99], off
	s_nop 1
	v_fmamk_f32 v96, v175, 0x3a800000, v226
	v_rsq_f32_e32 v96, v96
	v_or_b32_e32 v97, 32, v154
	v_mad_i64_i32 v[98:99], s[46:47], v97, s88, v[156:157]
	v_pk_fma_f32 v[88:89], v[96:97], v[88:89], v[242:243] op_sel_hi:[0,1,1]
	v_pk_fma_f32 v[92:93], v[96:97], v[92:93], v[246:247] op_sel_hi:[0,1,1]
	v_mul_f32_e32 v100, 0xbfb8aa3b, v88
	v_pk_fma_f32 v[94:95], v[96:97], v[94:95], v[248:249] op_sel_hi:[0,1,1]
	v_pk_fma_f32 v[90:91], v[96:97], v[90:91], v[244:245] op_sel_hi:[0,1,1]
	v_mul_f32_e32 v97, 0xbfb8aa3b, v92
	v_exp_f32_e32 v101, v100
	v_mul_f32_e32 v100, 0xbfb8aa3b, v93
	v_exp_f32_e32 v97, v97
	v_exp_f32_e32 v103, v100
	v_mul_f32_e32 v100, 0xbfb8aa3b, v89
	v_exp_f32_e32 v104, v100
	v_mul_f32_e32 v100, 0xbfb8aa3b, v94
	v_exp_f32_e32 v105, v100
	v_mul_f32_e32 v100, 0xbfb8aa3b, v90
	v_exp_f32_e32 v106, v100
	v_mul_f32_e32 v100, 0xbfb8aa3b, v95
	v_exp_f32_e32 v107, v100
	v_mul_f32_e32 v100, 0xbfb8aa3b, v91
	v_pk_fma_f32 v[86:87], v[96:97], v[86:87], v[240:241] op_sel_hi:[0,1,1]
	v_pk_fma_f32 v[84:85], v[96:97], v[84:85], v[238:239] op_sel_hi:[0,1,1]
	v_add_f32_e32 v97, 1.0, v97
	v_exp_f32_e32 v108, v100
	v_rcp_f32_e32 v100, v97
	v_add_f32_e32 v97, 1.0, v101
	v_rcp_f32_e32 v102, v97
	v_add_f32_e32 v97, 1.0, v103
	v_rcp_f32_e32 v101, v97
	v_add_f32_e32 v97, 1.0, v104
	v_rcp_f32_e32 v103, v97
	v_add_f32_e32 v97, 1.0, v105
	v_rcp_f32_e32 v104, v97
	v_add_f32_e32 v97, 1.0, v106
	v_rcp_f32_e32 v106, v97
	v_add_f32_e32 v97, 1.0, v107
	v_rcp_f32_e32 v105, v97
	v_add_f32_e32 v97, 1.0, v108
	v_rcp_f32_e32 v107, v97
	v_pk_fma_f32 v[82:83], v[96:97], v[82:83], v[236:237] op_sel_hi:[0,1,1]
	v_pk_fma_f32 v[80:81], v[96:97], v[80:81], v[234:235] op_sel_hi:[0,1,1]
	v_pk_mul_f32 v[86:87], v[94:95], v[86:87]
	v_pk_mul_f32 v[84:85], v[92:93], v[84:85]
	v_pk_mul_f32 v[82:83], v[90:91], v[82:83]
	v_pk_mul_f32 v[80:81], v[88:89], v[80:81]
	v_pk_mul_f32 v[86:87], v[86:87], v[104:105]
	v_pk_mul_f32 v[84:85], v[84:85], v[100:101]
	v_pk_mul_f32 v[88:89], v[82:83], v[106:107]
	v_pk_mul_f32 v[82:83], v[80:81], v[102:103]
	v_lshl_add_u64 v[98:99], v[98:99], 0, v[158:159]
	v_cvt_pk_bf16_f32 v80, v84, v85
	v_cvt_pk_bf16_f32 v81, v86, v87
	v_cvt_pk_bf16_f32 v82, v82, v83
	v_cvt_pk_bf16_f32 v83, v88, v89
	global_store_dwordx4 v[98:99], v[80:83], off
	s_nop 1
	v_fmamk_f32 v80, v174, 0x3a800000, v226
	v_rsq_f32_e32 v80, v80
	v_or_b32_e32 v81, 48, v154
	v_mad_i64_i32 v[82:83], s[46:47], v81, s88, v[156:157]
	v_pk_fma_f32 v[72:73], v[80:81], v[72:73], v[242:243] op_sel_hi:[0,1,1]
	v_pk_fma_f32 v[76:77], v[80:81], v[76:77], v[246:247] op_sel_hi:[0,1,1]
	v_mul_f32_e32 v84, 0xbfb8aa3b, v72
	v_pk_fma_f32 v[78:79], v[80:81], v[78:79], v[248:249] op_sel_hi:[0,1,1]
	v_pk_fma_f32 v[74:75], v[80:81], v[74:75], v[244:245] op_sel_hi:[0,1,1]
	v_mul_f32_e32 v81, 0xbfb8aa3b, v76
	v_exp_f32_e32 v85, v84
	v_mul_f32_e32 v84, 0xbfb8aa3b, v77
	v_exp_f32_e32 v81, v81
	v_exp_f32_e32 v87, v84
	v_mul_f32_e32 v84, 0xbfb8aa3b, v73
	v_exp_f32_e32 v88, v84
	v_mul_f32_e32 v84, 0xbfb8aa3b, v78
	v_exp_f32_e32 v89, v84
	v_mul_f32_e32 v84, 0xbfb8aa3b, v74
	v_exp_f32_e32 v90, v84
	v_mul_f32_e32 v84, 0xbfb8aa3b, v79
	v_exp_f32_e32 v91, v84
	v_mul_f32_e32 v84, 0xbfb8aa3b, v75
	v_pk_fma_f32 v[70:71], v[80:81], v[70:71], v[240:241] op_sel_hi:[0,1,1]
	v_pk_fma_f32 v[68:69], v[80:81], v[68:69], v[238:239] op_sel_hi:[0,1,1]
	v_add_f32_e32 v81, 1.0, v81
	v_exp_f32_e32 v92, v84
	v_rcp_f32_e32 v84, v81
	v_add_f32_e32 v81, 1.0, v85
	v_rcp_f32_e32 v86, v81
	v_add_f32_e32 v81, 1.0, v87
	v_rcp_f32_e32 v85, v81
	v_add_f32_e32 v81, 1.0, v88
	v_rcp_f32_e32 v87, v81
	v_add_f32_e32 v81, 1.0, v89
	v_rcp_f32_e32 v88, v81
	v_add_f32_e32 v81, 1.0, v90
	v_rcp_f32_e32 v90, v81
	v_add_f32_e32 v81, 1.0, v91
	v_rcp_f32_e32 v89, v81
	v_add_f32_e32 v81, 1.0, v92
	v_rcp_f32_e32 v91, v81
	v_pk_fma_f32 v[66:67], v[80:81], v[66:67], v[236:237] op_sel_hi:[0,1,1]
	v_pk_fma_f32 v[64:65], v[80:81], v[64:65], v[234:235] op_sel_hi:[0,1,1]
	v_pk_mul_f32 v[68:69], v[76:77], v[68:69]
	v_pk_mul_f32 v[66:67], v[74:75], v[66:67]
	v_pk_mul_f32 v[68:69], v[68:69], v[84:85]
	v_pk_mul_f32 v[64:65], v[72:73], v[64:65]
	v_pk_mul_f32 v[72:73], v[66:67], v[90:91]
	v_pk_mul_f32 v[66:67], v[64:65], v[86:87]
	v_cvt_pk_bf16_f32 v64, v68, v69
	v_fmamk_f32 v68, v167, 0x3a800000, v226
	v_rsq_f32_e32 v68, v68
	v_pk_mul_f32 v[70:71], v[78:79], v[70:71]
	v_lshl_add_u64 v[82:83], v[82:83], 0, v[158:159]
	v_pk_mul_f32 v[70:71], v[70:71], v[88:89]
	v_cvt_pk_bf16_f32 v66, v66, v67
	v_cvt_pk_bf16_f32 v65, v70, v71
	v_cvt_pk_bf16_f32 v67, v72, v73
	v_pk_fma_f32 v[56:57], v[68:69], v[56:57], v[242:243] op_sel_hi:[0,1,1]
	global_store_dwordx4 v[82:83], v[64:67], off
	v_pk_fma_f32 v[60:61], v[68:69], v[60:61], v[246:247] op_sel_hi:[0,1,1]
	v_pk_fma_f32 v[62:63], v[68:69], v[62:63], v[248:249] op_sel_hi:[0,1,1]
	v_mul_f32_e32 v67, 0xbfb8aa3b, v56
	v_pk_fma_f32 v[58:59], v[68:69], v[58:59], v[244:245] op_sel_hi:[0,1,1]
	v_exp_f32_e32 v67, v67
	v_mul_f32_e32 v69, 0xbfb8aa3b, v61
	v_mul_f32_e32 v70, 0xbfb8aa3b, v57
	v_exp_f32_e32 v69, v69
	v_exp_f32_e32 v71, v70
	v_mul_f32_e32 v70, 0xbfb8aa3b, v62
	v_exp_f32_e32 v72, v70
	v_mul_f32_e32 v70, 0xbfb8aa3b, v58
	v_exp_f32_e32 v73, v70
	v_mul_f32_e32 v70, 0xbfb8aa3b, v63
	v_mul_f32_e32 v66, 0xbfb8aa3b, v60
	v_exp_f32_e32 v75, v70
	v_mul_f32_e32 v70, 0xbfb8aa3b, v59
	v_add_f32_e32 v67, 1.0, v67
	v_exp_f32_e32 v66, v66
	v_exp_f32_e32 v76, v70
	v_pk_fma_f32 v[54:55], v[68:69], v[54:55], v[240:241] op_sel_hi:[0,1,1]
	v_pk_fma_f32 v[52:53], v[68:69], v[52:53], v[238:239] op_sel_hi:[0,1,1]
	v_rcp_f32_e32 v70, v67
	v_add_f32_e32 v67, 1.0, v69
	v_add_f32_e32 v69, 1.0, v71
	v_rcp_f32_e32 v71, v69
	v_add_f32_e32 v69, 1.0, v72
	v_rcp_f32_e32 v72, v69
	v_add_f32_e32 v69, 1.0, v73
	v_rcp_f32_e32 v74, v69
	v_add_f32_e32 v69, 1.0, v75
	v_add_f32_e32 v66, 1.0, v66
	v_rcp_f32_e32 v73, v69
	v_add_f32_e32 v69, 1.0, v76
	v_rcp_f32_e32 v66, v66
	v_rcp_f32_e32 v67, v67
	v_rcp_f32_e32 v75, v69
	v_pk_fma_f32 v[50:51], v[68:69], v[50:51], v[236:237] op_sel_hi:[0,1,1]
	v_pk_fma_f32 v[48:49], v[68:69], v[48:49], v[234:235] op_sel_hi:[0,1,1]
	v_pk_mul_f32 v[54:55], v[62:63], v[54:55]
	v_pk_mul_f32 v[52:53], v[60:61], v[52:53]
	v_pk_mul_f32 v[50:51], v[58:59], v[50:51]
	v_pk_mul_f32 v[48:49], v[56:57], v[48:49]
	v_mad_i64_i32 v[64:65], s[46:47], v173, s88, v[156:157]
	v_pk_mul_f32 v[54:55], v[54:55], v[72:73]
	v_pk_mul_f32 v[52:53], v[52:53], v[66:67]
	v_pk_mul_f32 v[56:57], v[50:51], v[74:75]
	v_pk_mul_f32 v[50:51], v[48:49], v[70:71]
	v_lshl_add_u64 v[64:65], v[64:65], 0, v[158:159]
	v_cvt_pk_bf16_f32 v48, v52, v53
	v_cvt_pk_bf16_f32 v49, v54, v55
	v_cvt_pk_bf16_f32 v50, v50, v51
	v_cvt_pk_bf16_f32 v51, v56, v57
	global_store_dwordx4 v[64:65], v[48:51], off
	s_nop 1
	v_fmamk_f32 v48, v166, 0x3a800000, v226
	v_rsq_f32_e32 v48, v48
	v_add_u32_e32 v49, 0x90, v154
	v_mad_i64_i32 v[50:51], s[46:47], v49, s88, v[156:157]
	v_pk_fma_f32 v[40:41], v[48:49], v[40:41], v[242:243] op_sel_hi:[0,1,1]
	v_pk_fma_f32 v[44:45], v[48:49], v[44:45], v[246:247] op_sel_hi:[0,1,1]
	v_mul_f32_e32 v52, 0xbfb8aa3b, v40
	v_pk_fma_f32 v[46:47], v[48:49], v[46:47], v[248:249] op_sel_hi:[0,1,1]
	v_pk_fma_f32 v[42:43], v[48:49], v[42:43], v[244:245] op_sel_hi:[0,1,1]
	v_mul_f32_e32 v49, 0xbfb8aa3b, v44
	v_exp_f32_e32 v53, v52
	v_mul_f32_e32 v52, 0xbfb8aa3b, v45
	v_exp_f32_e32 v49, v49
	v_exp_f32_e32 v55, v52
	v_mul_f32_e32 v52, 0xbfb8aa3b, v41
	v_exp_f32_e32 v56, v52
	v_mul_f32_e32 v52, 0xbfb8aa3b, v46
	v_exp_f32_e32 v57, v52
	v_mul_f32_e32 v52, 0xbfb8aa3b, v42
	v_exp_f32_e32 v58, v52
	v_mul_f32_e32 v52, 0xbfb8aa3b, v47
	v_exp_f32_e32 v59, v52
	v_mul_f32_e32 v52, 0xbfb8aa3b, v43
	v_pk_fma_f32 v[38:39], v[48:49], v[38:39], v[240:241] op_sel_hi:[0,1,1]
	v_pk_fma_f32 v[36:37], v[48:49], v[36:37], v[238:239] op_sel_hi:[0,1,1]
	v_add_f32_e32 v49, 1.0, v49
	v_exp_f32_e32 v60, v52
	v_rcp_f32_e32 v52, v49
	v_add_f32_e32 v49, 1.0, v53
	v_rcp_f32_e32 v54, v49
	v_add_f32_e32 v49, 1.0, v55
	v_rcp_f32_e32 v53, v49
	v_add_f32_e32 v49, 1.0, v56
	v_rcp_f32_e32 v55, v49
	v_add_f32_e32 v49, 1.0, v57
	v_rcp_f32_e32 v56, v49
	v_add_f32_e32 v49, 1.0, v58
	v_rcp_f32_e32 v58, v49
	v_add_f32_e32 v49, 1.0, v59
	v_rcp_f32_e32 v57, v49
	v_add_f32_e32 v49, 1.0, v60
	v_rcp_f32_e32 v59, v49
	v_pk_fma_f32 v[34:35], v[48:49], v[34:35], v[236:237] op_sel_hi:[0,1,1]
	v_pk_fma_f32 v[32:33], v[48:49], v[32:33], v[234:235] op_sel_hi:[0,1,1]
	v_pk_mul_f32 v[38:39], v[46:47], v[38:39]
	v_pk_mul_f32 v[36:37], v[44:45], v[36:37]
	v_pk_mul_f32 v[34:35], v[42:43], v[34:35]
	v_pk_mul_f32 v[32:33], v[40:41], v[32:33]
	v_pk_mul_f32 v[38:39], v[38:39], v[56:57]
	v_pk_mul_f32 v[36:37], v[36:37], v[52:53]
	v_pk_mul_f32 v[40:41], v[34:35], v[58:59]
	v_pk_mul_f32 v[34:35], v[32:33], v[54:55]
	v_lshl_add_u64 v[50:51], v[50:51], 0, v[158:159]
	v_cvt_pk_bf16_f32 v32, v36, v37
	v_cvt_pk_bf16_f32 v33, v38, v39
	v_cvt_pk_bf16_f32 v34, v34, v35
	v_cvt_pk_bf16_f32 v35, v40, v41
	global_store_dwordx4 v[50:51], v[32:35], off
	s_nop 1
	v_fmamk_f32 v32, v165, 0x3a800000, v226
	v_rsq_f32_e32 v32, v32
	v_add_u32_e32 v33, 0xa0, v154
	v_mad_i64_i32 v[34:35], s[46:47], v33, s88, v[156:157]
	v_pk_fma_f32 v[24:25], v[32:33], v[24:25], v[242:243] op_sel_hi:[0,1,1]
	v_pk_fma_f32 v[28:29], v[32:33], v[28:29], v[246:247] op_sel_hi:[0,1,1]
	v_mul_f32_e32 v36, 0xbfb8aa3b, v24
	v_pk_fma_f32 v[30:31], v[32:33], v[30:31], v[248:249] op_sel_hi:[0,1,1]
	v_pk_fma_f32 v[26:27], v[32:33], v[26:27], v[244:245] op_sel_hi:[0,1,1]
	v_mul_f32_e32 v33, 0xbfb8aa3b, v28
	v_exp_f32_e32 v37, v36
	v_mul_f32_e32 v36, 0xbfb8aa3b, v29
	v_exp_f32_e32 v33, v33
	v_exp_f32_e32 v39, v36
	v_mul_f32_e32 v36, 0xbfb8aa3b, v25
	v_exp_f32_e32 v40, v36
	v_mul_f32_e32 v36, 0xbfb8aa3b, v30
	v_exp_f32_e32 v41, v36
	v_mul_f32_e32 v36, 0xbfb8aa3b, v26
	v_exp_f32_e32 v42, v36
	v_mul_f32_e32 v36, 0xbfb8aa3b, v31
	v_exp_f32_e32 v43, v36
	v_mul_f32_e32 v36, 0xbfb8aa3b, v27
	v_pk_fma_f32 v[22:23], v[32:33], v[22:23], v[240:241] op_sel_hi:[0,1,1]
	v_pk_fma_f32 v[20:21], v[32:33], v[20:21], v[238:239] op_sel_hi:[0,1,1]
	v_add_f32_e32 v33, 1.0, v33
	v_exp_f32_e32 v44, v36
	v_rcp_f32_e32 v36, v33
	v_add_f32_e32 v33, 1.0, v37
	v_rcp_f32_e32 v38, v33
	v_add_f32_e32 v33, 1.0, v39
	v_rcp_f32_e32 v37, v33
	v_add_f32_e32 v33, 1.0, v40
	v_rcp_f32_e32 v39, v33
	v_add_f32_e32 v33, 1.0, v41
	v_rcp_f32_e32 v40, v33
	v_add_f32_e32 v33, 1.0, v42
	v_rcp_f32_e32 v42, v33
	v_add_f32_e32 v33, 1.0, v43
	v_rcp_f32_e32 v41, v33
	v_add_f32_e32 v33, 1.0, v44
	v_rcp_f32_e32 v43, v33
	v_pk_fma_f32 v[18:19], v[32:33], v[18:19], v[236:237] op_sel_hi:[0,1,1]
	v_pk_fma_f32 v[16:17], v[32:33], v[16:17], v[234:235] op_sel_hi:[0,1,1]
	v_pk_mul_f32 v[22:23], v[30:31], v[22:23]
	v_pk_mul_f32 v[20:21], v[28:29], v[20:21]
	v_pk_mul_f32 v[18:19], v[26:27], v[18:19]
	v_pk_mul_f32 v[16:17], v[24:25], v[16:17]
	v_pk_mul_f32 v[22:23], v[22:23], v[40:41]
	v_pk_mul_f32 v[20:21], v[20:21], v[36:37]
	v_pk_mul_f32 v[24:25], v[18:19], v[42:43]
	v_pk_mul_f32 v[18:19], v[16:17], v[38:39]
	v_lshl_add_u64 v[34:35], v[34:35], 0, v[158:159]
	v_cvt_pk_bf16_f32 v16, v20, v21
	v_cvt_pk_bf16_f32 v17, v22, v23
	v_cvt_pk_bf16_f32 v18, v18, v19
	v_cvt_pk_bf16_f32 v19, v24, v25
	global_store_dwordx4 v[34:35], v[16:19], off
	s_nop 1
	v_fmamk_f32 v16, v155, 0x3a800000, v226
	v_rsq_f32_e32 v16, v16
	v_add_u32_e32 v17, 0xb0, v154
	v_mad_i64_i32 v[18:19], s[46:47], v17, s88, v[156:157]
	v_pk_fma_f32 v[8:9], v[16:17], v[8:9], v[242:243] op_sel_hi:[0,1,1]
	v_pk_fma_f32 v[12:13], v[16:17], v[12:13], v[246:247] op_sel_hi:[0,1,1]
	v_mul_f32_e32 v20, 0xbfb8aa3b, v8
	v_pk_fma_f32 v[14:15], v[16:17], v[14:15], v[248:249] op_sel_hi:[0,1,1]
	v_pk_fma_f32 v[10:11], v[16:17], v[10:11], v[244:245] op_sel_hi:[0,1,1]
	v_mul_f32_e32 v17, 0xbfb8aa3b, v12
	v_exp_f32_e32 v21, v20
	v_mul_f32_e32 v20, 0xbfb8aa3b, v13
	v_exp_f32_e32 v17, v17
	v_exp_f32_e32 v23, v20
	v_mul_f32_e32 v20, 0xbfb8aa3b, v9
	v_exp_f32_e32 v24, v20
	v_mul_f32_e32 v20, 0xbfb8aa3b, v14
	v_exp_f32_e32 v25, v20
	v_mul_f32_e32 v20, 0xbfb8aa3b, v10
	v_exp_f32_e32 v26, v20
	v_mul_f32_e32 v20, 0xbfb8aa3b, v15
	v_exp_f32_e32 v27, v20
	v_mul_f32_e32 v20, 0xbfb8aa3b, v11
	v_pk_fma_f32 v[6:7], v[16:17], v[6:7], v[240:241] op_sel_hi:[0,1,1]
	v_pk_fma_f32 v[4:5], v[16:17], v[4:5], v[238:239] op_sel_hi:[0,1,1]
	v_add_f32_e32 v17, 1.0, v17
	v_exp_f32_e32 v28, v20
	v_rcp_f32_e32 v20, v17
	v_add_f32_e32 v17, 1.0, v21
	v_rcp_f32_e32 v22, v17
	v_add_f32_e32 v17, 1.0, v23
	v_rcp_f32_e32 v21, v17
	v_add_f32_e32 v17, 1.0, v24
	v_rcp_f32_e32 v23, v17
	v_add_f32_e32 v17, 1.0, v25
	v_rcp_f32_e32 v24, v17
	v_add_f32_e32 v17, 1.0, v26
	v_rcp_f32_e32 v26, v17
	v_add_f32_e32 v17, 1.0, v27
	v_rcp_f32_e32 v25, v17
	v_add_f32_e32 v17, 1.0, v28
	v_rcp_f32_e32 v27, v17
	v_pk_fma_f32 v[2:3], v[16:17], v[2:3], v[236:237] op_sel_hi:[0,1,1]
	v_pk_fma_f32 v[0:1], v[16:17], v[0:1], v[234:235] op_sel_hi:[0,1,1]
	v_pk_mul_f32 v[6:7], v[14:15], v[6:7]
	v_pk_mul_f32 v[4:5], v[12:13], v[4:5]
	v_pk_mul_f32 v[2:3], v[10:11], v[2:3]
	v_pk_mul_f32 v[0:1], v[8:9], v[0:1]
	v_pk_mul_f32 v[6:7], v[6:7], v[24:25]
	v_pk_mul_f32 v[4:5], v[4:5], v[20:21]
	v_pk_mul_f32 v[8:9], v[2:3], v[26:27]
	v_pk_mul_f32 v[2:3], v[0:1], v[22:23]
	v_lshl_add_u64 v[18:19], v[18:19], 0, v[158:159]
	v_cvt_pk_bf16_f32 v0, v4, v5
	v_cvt_pk_bf16_f32 v1, v6, v7
	v_cvt_pk_bf16_f32 v2, v2, v3
	v_cvt_pk_bf16_f32 v3, v8, v9
	global_store_dwordx4 v[18:19], v[0:3], off
	s_cbranch_vccnz .LBB0_728
	s_andn2_b64 vcc, exec, s[10:11]
	s_cbranch_vccnz .LBB0_727
	s_barrier
	s_branch .LBB0_727
